# XCD-local barriers: L1 invalidate at barrier entry, release atomic not waited
# speedup vs baseline: 1.0049x; 1.0049x over previous
.LBB0_426:
	s_and_b64 vcc, exec, s[38:39]
	s_cbranch_vccz .LBB0_446
	s_waitcnt vmcnt(0)
	s_barrier
	s_mov_b64 s[38:39], exec
	v_readlane_b32 s20, v254, 3
	v_readlane_b32 s21, v254, 4
	s_and_b64 s[20:21], s[38:39], s[20:21]
	s_mov_b64 exec, s[20:21]
	s_cbranch_execz .LBB0_445
	s_add_i32 s6, 0, 0x21000
	s_waitcnt vmcnt(7)
	v_mov_b32_e32 v0, s6
	buffer_inv sc1
	s_waitcnt lgkmcnt(0)
	ds_read_b32 v0, v0
	s_mov_b64 s[40:41], exec
	v_mbcnt_lo_u32_b32 v1, s40, 0
	v_mbcnt_hi_u32_b32 v1, s41, v1
	v_cmp_eq_u32_e32 vcc, 0, v1
	s_and_saveexec_b64 s[42:43], vcc
	s_cbranch_execz .LBB0_430
	s_bcnt1_i32_b64 s6, s[40:41]
	v_readlane_b32 s20, v254, 61
	v_mov_b32_e32 v2, s6
	v_readlane_b32 s21, v254, 62
	s_nop 4
	global_atomic_add v2, v49, v2, s[20:21] sc0

.LBB0_444:
	s_or_b64 exec, exec, s[40:41]
	s_waitcnt vmcnt(1)
	s_waitcnt vmcnt(1)

.LBB0_550:
	s_and_b64 vcc, exec, s[38:39]
	s_cbranch_vccz .LBB0_570
	s_waitcnt vmcnt(0)
	s_barrier
	s_mov_b64 s[38:39], exec
	v_readlane_b32 s20, v254, 3
	v_readlane_b32 s21, v254, 4
	s_and_b64 s[20:21], s[38:39], s[20:21]
	s_mov_b64 exec, s[20:21]
	s_cbranch_execz .LBB0_569
	s_add_i32 s6, 0, 0x21000
	v_mov_b32_e32 v0, s6
	buffer_inv sc1
	s_waitcnt lgkmcnt(0)
	ds_read_b32 v0, v0
	s_mov_b64 s[40:41], exec
	v_mbcnt_lo_u32_b32 v1, s40, 0
	v_mbcnt_hi_u32_b32 v1, s41, v1
	v_cmp_eq_u32_e32 vcc, 0, v1
	s_and_saveexec_b64 s[42:43], vcc
	s_cbranch_execz .LBB0_554
	s_bcnt1_i32_b64 s6, s[40:41]
	v_readlane_b32 s20, v254, 61
	v_mov_b32_e32 v2, s6
	v_readlane_b32 s21, v254, 62
	s_nop 4
	global_atomic_add v2, v49, v2, s[20:21] sc0

.LBB0_752:
	s_and_b64 vcc, exec, s[40:41]
	s_cbranch_vccz .LBB0_772
	s_waitcnt vmcnt(0)
	s_barrier
	s_mov_b64 s[40:41], exec
	v_readlane_b32 s8, v254, 3
	v_readlane_b32 s9, v254, 4
	s_and_b64 s[8:9], s[40:41], s[8:9]
	s_mov_b64 exec, s[8:9]
	s_cbranch_execz .LBB0_771
	s_add_i32 s6, 0, 0x21000
	v_mov_b32_e32 v0, s6
	buffer_inv sc1
	s_waitcnt lgkmcnt(0)
	ds_read_b32 v0, v0
	s_mov_b64 s[42:43], exec
	v_mbcnt_lo_u32_b32 v1, s42, 0
	v_mbcnt_hi_u32_b32 v1, s43, v1
	v_cmp_eq_u32_e32 vcc, 0, v1
	s_and_saveexec_b64 s[44:45], vcc
	s_cbranch_execz .LBB0_756
	s_bcnt1_i32_b64 s6, s[42:43]
	v_readlane_b32 s8, v254, 61
	v_mov_b32_e32 v2, s6
	v_readlane_b32 s9, v254, 62
	s_nop 4
	global_atomic_add v2, v49, v2, s[8:9] sc0

.LBB0_770:
	s_or_b64 exec, exec, s[42:43]
	s_waitcnt vmcnt(1)
	s_waitcnt vmcnt(1)

.LBB0_1008:
	s_and_b64 vcc, exec, s[40:41]
	s_cbranch_vccz .LBB0_1028
	s_waitcnt vmcnt(0)
	s_barrier
	s_mov_b64 s[40:41], exec
	v_readlane_b32 s6, v254, 3
	v_readlane_b32 s7, v254, 4
	s_and_b64 s[6:7], s[40:41], s[6:7]
	s_mov_b64 exec, s[6:7]
	s_cbranch_execz .LBB0_1027
	s_add_i32 s6, 0, 0x21000
	v_mov_b32_e32 v0, s6
	buffer_inv sc1
	s_waitcnt lgkmcnt(0)
	ds_read_b32 v0, v0
	s_mov_b64 s[42:43], exec
	v_mbcnt_lo_u32_b32 v1, s42, 0
	v_mbcnt_hi_u32_b32 v1, s43, v1
	v_cmp_eq_u32_e32 vcc, 0, v1
	s_and_saveexec_b64 s[44:45], vcc
	s_cbranch_execz .LBB0_1012
	s_bcnt1_i32_b64 s6, s[42:43]
	v_mov_b32_e32 v2, s6
	v_readlane_b32 s6, v254, 61
	v_readlane_b32 s7, v254, 62
	s_nop 4
	global_atomic_add v2, v49, v2, s[6:7] sc0

.LBB0_1175:
	s_and_b64 vcc, exec, s[38:39]
	v_readlane_b32 s73, v255, 21
	s_cbranch_vccz .LBB0_1195
	s_waitcnt vmcnt(0)
	s_barrier
	s_mov_b64 s[38:39], exec
	v_readlane_b32 s6, v254, 3
	v_readlane_b32 s7, v254, 4
	s_and_b64 s[6:7], s[38:39], s[6:7]
	s_mov_b64 exec, s[6:7]
	s_cbranch_execz .LBB0_1194
	s_add_i32 s6, 0, 0x21000
	v_mov_b32_e32 v0, s6
	buffer_inv sc1
	s_waitcnt lgkmcnt(0)
	ds_read_b32 v0, v0
	s_mov_b64 s[40:41], exec
	v_mbcnt_lo_u32_b32 v1, s40, 0
	v_mbcnt_hi_u32_b32 v1, s41, v1
	v_cmp_eq_u32_e32 vcc, 0, v1
	s_and_saveexec_b64 s[42:43], vcc
	s_cbranch_execz .LBB0_1179
	s_bcnt1_i32_b64 s6, s[40:41]
	v_mov_b32_e32 v2, s6
	v_readlane_b32 s6, v254, 61
	v_readlane_b32 s7, v254, 62
	s_nop 4
	global_atomic_add v2, v49, v2, s[6:7] sc0

.LBB0_1259:
	s_and_b64 vcc, exec, s[2:3]
	s_cbranch_vccz .LBB0_1279
	s_waitcnt vmcnt(0)
	s_barrier
	s_mov_b64 s[2:3], exec
	v_readlane_b32 s6, v254, 3
	v_readlane_b32 s7, v254, 4
	s_and_b64 s[6:7], s[2:3], s[6:7]
	s_mov_b64 exec, s[6:7]
	s_cbranch_execz .LBB0_1278
	s_add_i32 s6, 0, 0x21000
	v_mov_b32_e32 v0, s6
	buffer_inv sc1
	s_waitcnt lgkmcnt(0)
	ds_read_b32 v0, v0
	s_mov_b64 s[38:39], exec
	v_mbcnt_lo_u32_b32 v1, s38, 0
	v_mbcnt_hi_u32_b32 v1, s39, v1
	v_cmp_eq_u32_e32 vcc, 0, v1
	s_and_saveexec_b64 s[40:41], vcc
	s_cbranch_execz .LBB0_1263
	s_bcnt1_i32_b64 s6, s[38:39]
	v_mov_b32_e32 v2, s6
	v_readlane_b32 s6, v254, 61
	v_readlane_b32 s7, v254, 62
	s_nop 4
	global_atomic_add v2, v49, v2, s[6:7] sc0

.LBB0_1277:
	s_or_b64 exec, exec, s[38:39]
	s_waitcnt vmcnt(1)
	s_waitcnt vmcnt(1)

.LBB0_1379:
	s_and_b64 vcc, exec, s[2:3]
	s_cbranch_vccz .LBB0_1399
	s_waitcnt vmcnt(0)
	s_barrier
	s_mov_b64 s[2:3], exec
	v_readlane_b32 s8, v254, 3
	v_readlane_b32 s9, v254, 4
	s_and_b64 s[8:9], s[2:3], s[8:9]
	s_mov_b64 exec, s[8:9]
	s_cbranch_execz .LBB0_1398
	s_add_i32 s6, 0, 0x21000
	v_mov_b32_e32 v0, s6
	buffer_inv sc1
	s_waitcnt lgkmcnt(0)
	ds_read_b32 v0, v0
	s_mov_b64 s[38:39], exec
	v_mbcnt_lo_u32_b32 v1, s38, 0
	v_mbcnt_hi_u32_b32 v1, s39, v1
	v_cmp_eq_u32_e32 vcc, 0, v1
	s_and_saveexec_b64 s[40:41], vcc
	s_cbranch_execz .LBB0_1383
	s_bcnt1_i32_b64 s6, s[38:39]
	v_readlane_b32 s8, v254, 61
	v_mov_b32_e32 v2, s6
	v_readlane_b32 s9, v254, 62
	s_nop 4
	global_atomic_add v2, v49, v2, s[8:9] sc0

.LBB0_1934:
	s_and_b64 vcc, exec, s[2:3]
	s_cbranch_vccz .LBB0_1954
	s_waitcnt vmcnt(0)
	s_barrier
	s_mov_b64 s[2:3], exec
	v_readlane_b32 s8, v254, 3
	v_readlane_b32 s9, v254, 4
	s_and_b64 s[8:9], s[2:3], s[8:9]
	s_mov_b64 exec, s[8:9]
	s_cbranch_execz .LBB0_1953
	s_add_i32 s6, 0, 0x21000
	s_waitcnt vmcnt(7)
	v_mov_b32_e32 v0, s6
	buffer_inv sc1
	s_waitcnt lgkmcnt(0)
	ds_read_b32 v0, v0
	s_mov_b64 s[38:39], exec
	v_mbcnt_lo_u32_b32 v1, s38, 0
	v_mbcnt_hi_u32_b32 v1, s39, v1
	v_cmp_eq_u32_e32 vcc, 0, v1
	s_and_saveexec_b64 s[40:41], vcc
	s_cbranch_execz .LBB0_1938
	s_bcnt1_i32_b64 s6, s[38:39]
	v_readlane_b32 s8, v254, 61
	v_mov_b32_e32 v2, s6
	v_readlane_b32 s9, v254, 62
	s_nop 4
	global_atomic_add v2, v49, v2, s[8:9] sc0
